# phase header: grid-size load, kernarg pointer load and the two census LDS reads issued together behind one wait (29 phases)
# baseline (speedup 1.0000x reference)
; #define LAS __attribute__((address_space(3)))
; template <class T> __device__ __forceinline__ T* as_global(T* p) { __attribute__((address_space(1))) T* g = (__attribute__((address_space(1))) T*)p; asm volatile("" : "+s"(g)); return (T*)g; }
; __global__ void __launch_bounds__(512, 2) fwd_kernel(Args args) {
;     ...
;     for (int ph = args.ph_lo; ph < args.ph_hi; ++ph) {
;         const __attribute__((address_space(4))) Args* ap = (const __attribute__((address_space(4))) Args*)__builtin_amdgcn_kernarg_segment_ptr(); asm volatile("" : "+s"(ap));
;         int tid = threadIdx.x; asm volatile("" : "+v"(tid));
;         const int lane = tid & 63, wave = __builtin_amdgcn_readfirstlane(tid >> 6);
;         int Gd = gridDim.x, bx = blockIdx.x; asm volatile("" : "+s"(Gd), "+s"(bx));
;         const int gw = bx * 8 + wave, NGW = Gd * 8, gtid = bx * 512 + tid, NT = Gd * 512;
;         unsigned char* ws = ap->ws; asm volatile("" : "+s"(ws)); ws = as_global(ws);
;         bf16_t* PBF = (bf16_t*)(ws + WS_PBF); float* LSE = (float*)(ws + WS_LSE); bf16_t* BIG = (bf16_t*)(ws + WS_BIG);
;         pg8::ssq_t* SSQ = (pg8::ssq_t*)(ws + WS_SSQ);
;         float* H = as_global(ap->out);
;         const int type = c_prog[ph][0], layer = c_prog[ph][1];
;         int zoff = 0; asm volatile("" : "+v"(zoff));
;         const volatile LAS unsigned* stw = (const volatile LAS unsigned*)(lds + 131072 + zoff);
;         const bool uni = __builtin_amdgcn_readfirstlane((int)stw[3]) != 0 && Gd == 256;
;         const int xrank = __builtin_amdgcn_readfirstlane((int)stw[2]), xcc = (int)xbar.x;
;         bf16_t* HBin = (bf16_t*)(ws + (c_hb_in[layer] ? WS_X1 : WS_X0)); bf16_t* HBmid = (bf16_t*)(ws + (c_hb_mid[layer] ? WS_X1 : WS_X0)); bf16_t* HBoth = (bf16_t*)(ws + (c_hb_mid[layer] ? WS_X0 : WS_X1));
.LBB0_8:
	s_mov_b64 s[60:61], s[78:79]
	v_mov_b32_e32 v170, v222
	s_load_dword s0, s[84:85], 0x0
	s_load_dwordx4 s[68:71], s[60:61], 0xb8
	s_mov_b32 s5, s2
	v_mov_b32_e32 v0, v169
	v_readfirstlane_b32 s1, v170
	s_ashr_i32 s63, s1, 6
	v_add_u32_e32 v0, s3, v0
	ds_read_b32 v1, v0 offset:12
	ds_read_b32 v0, v0 offset:8
	s_waitcnt lgkmcnt(0)
	s_mov_b32 s6, s0
	v_writelane_b32 v255, s0, 30
	s_lshl_b32 s1, s5, 3
	s_lshl_b32 s77, s6, 3
	s_mov_b32 s8, s74
	s_mov_b32 s13, s95
	v_readfirstlane_b32 s0, v1
	v_readfirstlane_b32 s4, v0
	v_mov_b32_e32 v2, 0x19f80000
	v_mov_b32_e32 v3, 0x6c80000
	v_writelane_b32 v255, s4, 31
	v_writelane_b32 v255, s5, 32
	s_add_i32 s4, s1, s63
	v_writelane_b32 v255, s4, 33
	v_and_b32_e32 v126, 63, v170
	s_nop 0
	v_writelane_b32 v255, s5, 34
	s_add_u32 s4, s70, 0xac80000
	s_addc_u32 s5, s71, 0
	s_add_u32 s10, s70, 0xbf80000
	s_addc_u32 s11, s71, 0
	v_writelane_b32 v255, s10, 35
	s_add_u32 s1, s70, 0x1df80000
	s_nop 0
	v_writelane_b32 v255, s11, 36
	v_writelane_b32 v255, s1, 37
	s_addc_u32 s1, s71, 0
	v_writelane_b32 v255, s1, 38
	s_ashr_i32 s9, s74, 31
	s_mov_b32 s10, s74
	v_writelane_b32 v255, s10, 39
	s_lshl_b64 s[8:9], s[8:9], 1
	s_nop 0
	v_writelane_b32 v255, s11, 40
	s_getpc_b64 s[10:11]
	s_add_u32 s10, s10, c_prog@rel32@lo+4
	s_addc_u32 s11, s11, c_prog@rel32@hi+12
	s_and_b32 s7, s8, -4
	s_load_dword s7, s[10:11], s7
	s_waitcnt vmcnt(0) lgkmcnt(0)
	s_bitcmp1_b32 s8, 1
	s_cselect_b32 s1, 16, 0
	s_lshr_b32 s7, s7, s1
	s_and_b32 s7, s7, 0xffff
	s_and_b32 s1, 0xffff, s7
	s_lshr_b32 s12, s1, 8
	s_cmp_lg_u32 s0, 0
	s_cselect_b64 s[0:1], -1, 0
	s_cmpk_eq_i32 s6, 0x100
	s_cselect_b64 s[8:9], -1, 0
	s_cmp_eq_u32 s12, 1
	s_cselect_b32 s10, 1, 0
	s_add_i32 s11, s12, -1
	s_cmp_lt_u32 s11, 2
	s_cselect_b32 s11, 1, 0
	v_mov_b32_e32 v1, s10
	v_mov_b32_e32 v0, s11
	v_writelane_b32 v255, s12, 41
	s_and_b64 s[0:1], s[0:1], s[8:9]
	v_cmp_eq_u32_sdwa vcc, v1, v169 src0_sel:WORD_0 src1_sel:DWORD
	v_writelane_b32 v255, s13, 42
	v_writelane_b32 v255, s0, 43
	v_cndmask_b32_e32 v168, v2, v3, vcc
	v_lshl_add_u64 v[116:117], s[70:71], 0, v[168:169]
	v_writelane_b32 v255, s1, 44
	v_cmp_eq_u32_sdwa s[0:1], v0, v169 src0_sel:WORD_0 src1_sel:DWORD
	s_nop 1
	v_writelane_b32 v255, s0, 45
	s_nop 1
	v_writelane_b32 v255, s1, 46
	s_and_b64 s[0:1], s[0:1], exec
	s_cselect_b32 s0, s73, 0x19f80000
	s_add_u32 s0, s70, s0
	s_addc_u32 s1, s71, 0
	v_writelane_b32 v255, s0, 47
	s_nop 1
	v_writelane_b32 v255, s1, 48
	s_add_u32 s0, s70, 0x1e2c0000
	s_addc_u32 s1, s71, 0
	v_writelane_b32 v255, s0, 49
	s_nop 1
	v_writelane_b32 v255, s1, 50
	v_writelane_b32 v255, s60, 51
	s_and_b32 s0, s7, 0xff
	s_cmp_lt_i32 s0, 8
	v_writelane_b32 v255, s61, 52
	v_writelane_b32 v255, s0, 53
	s_cbranch_scc1 .LBB0_15
	s_and_b32 s0, 0xffff, s0
	v_writelane_b32 v255, s0, 54
	s_cmp_lt_i32 s0, 12
	s_mov_b64 s[10:11], -1
	s_cbranch_scc1 .LBB0_34
	v_readlane_b32 s0, v255, 54
	s_cmp_lt_i32 s0, 14
	s_mov_b64 s[8:9], -1
	s_cbranch_scc1 .LBB0_27
	s_mov_b64 s[36:37], -1
	s_cmp_lt_i32 s0, 15
	s_cbranch_scc1 .LBB0_24
	s_cmp_eq_u32 s0, 15
	s_cbranch_scc0 .LBB0_23
	v_readlane_b32 s0, v255, 31
	s_lshl_b32 s7, s0, 3
	v_readlane_b32 s0, v255, 17
	s_lshl_b32 s8, s0, 12
	v_readlane_b32 s12, v255, 43
	s_add_i32 s9, s8, 0x1000
	v_readlane_b32 s13, v255, 44
	s_and_b64 s[0:1], s[12:13], exec
	s_cselect_b32 s0, s9, 0x8000
	s_add_i32 s1, s63, s8
	s_add_i32 s1, s1, s7
	s_and_b64 s[8:9], s[12:13], exec
	v_readlane_b32 s8, v255, 33
	s_cselect_b32 s8, s1, s8
	s_load_dwordx2 s[10:11], s[60:61], 0x30
	s_cmp_ge_i32 s8, s0
	v_readlane_b32 s9, v255, 34
	s_waitcnt lgkmcnt(0)
	s_cbranch_scc1 .LBB0_23
	v_lshlrev_b32_e32 v168, 4, v126
	global_load_dwordx4 v[0:3], v168, s[10:11]
	global_load_dwordx4 v[4:7], v168, s[10:11] offset:1024
	global_load_dwordx4 v[8:11], v168, s[10:11] offset:2048
	global_load_dwordx4 v[12:15], v168, s[10:11] offset:3072
	v_cmp_lt_i32_e32 vcc, v229, v228
	v_readlane_b32 s10, v255, 43
	v_readlane_b32 s11, v255, 44
	v_cndmask_b32_e32 v18, v225, v229, vcc
	v_cmp_lt_i32_e32 vcc, v230, v228
	v_lshlrev_b32_e32 v70, 2, v18
	s_and_b64 s[10:11], s[10:11], exec
	v_cndmask_b32_e32 v18, v225, v230, vcc
	v_cmp_lt_i32_e32 vcc, v231, v228
	v_lshlrev_b32_e32 v71, 2, v18
	v_lshlrev_b32_e32 v16, 3, v126
	v_cndmask_b32_e32 v18, v225, v231, vcc
	v_cmp_lt_i32_e32 vcc, v232, v228
	v_lshlrev_b32_e32 v72, 2, v18
	v_mov_b32_e32 v17, v169
	v_cndmask_b32_e32 v18, v225, v232, vcc
	v_cmp_lt_i32_e32 vcc, v233, v228
	v_lshlrev_b32_e32 v73, 2, v18
	s_cselect_b32 s1, 0x100, s77
	v_cndmask_b32_e32 v18, v225, v233, vcc
	v_cmp_lt_i32_e32 vcc, v234, v228
	v_lshl_add_u64 v[16:17], s[70:71], 0, v[16:17]
	s_mov_b64 s[10:11], 0x19f80000
	v_lshlrev_b32_e32 v74, 2, v18
	v_cndmask_b32_e32 v18, v225, v234, vcc
	s_add_i32 s7, s0, -1
	v_lshl_add_u64 v[16:17], v[16:17], 0, s[10:11]
	v_lshlrev_b32_e32 v75, 2, v18
	v_lshl_add_u64 v[18:19], s[68:69], 0, v[168:169]
	s_lshl_b32 s16, s1, 1
	s_branch .LBB0_17
